# router phase row loop: lane-swap VALU ops for the cross-lane adds instead of LDS permutes, partial reads issued together, counted waits for the prefetched rows (also restores the wait the peeled step
# speedup vs baseline: 1.0021x; 1.0021x over previous
.LBB0_797:
	s_and_saveexec_b64 s[8:9], s[2:3]
	ds_write_b32 v144, v213 offset:38400
	s_or_b64 exec, exec, s[8:9]
	s_lshl_b32 s15, s14, 7
	v_or_b32_e32 v156, s15, v145
	v_ashrrev_i32_e32 v157, 31, v156
	v_lshlrev_b64 v[128:129], 11, v[156:157]
	v_lshl_add_u64 v[128:129], v[146:147], 0, v[128:129]
	global_load_dwordx4 v[140:143], v[128:129], off
	global_load_dwordx4 v[136:139], v[128:129], off offset:64
	global_load_dwordx4 v[132:135], v[128:129], off offset:128
	s_nop 0
	global_load_dwordx4 v[128:131], v[128:129], off offset:192
	s_mov_b32 s22, 0
	v_mov_b32_e32 v158, v220
	s_waitcnt vmcnt(0)
	s_branch .LBB0_801

.LBB0_801:
	v_ashrrev_i32_e32 v159, 31, v158
	s_waitcnt vmcnt(4)
	v_lshlrev_b32_e32 v200, 16, v128
	v_and_b32_e32 v201, 0xffff0000, v128
	v_lshlrev_b32_e32 v206, 16, v129
	v_and_b32_e32 v207, 0xffff0000, v129
	v_lshlrev_b64 v[128:129], 11, v[158:159]
	v_lshl_add_u64 v[128:129], v[146:147], 0, v[128:129]
	v_add_co_u32_e32 v128, vcc, s72, v128
	v_lshlrev_b32_e32 v160, 16, v140
	s_nop 0
	v_addc_co_u32_e32 v129, vcc, 0, v129, vcc
	v_and_b32_e32 v161, 0xffff0000, v140
	v_lshlrev_b32_e32 v164, 16, v141
	v_and_b32_e32 v165, 0xffff0000, v141
	v_lshlrev_b32_e32 v162, 16, v142
	v_and_b32_e32 v163, 0xffff0000, v142
	v_lshlrev_b32_e32 v170, 16, v143
	v_and_b32_e32 v171, 0xffff0000, v143
	v_lshlrev_b32_e32 v166, 16, v136
	v_and_b32_e32 v167, 0xffff0000, v136
	v_lshlrev_b32_e32 v174, 16, v137
	v_and_b32_e32 v175, 0xffff0000, v137
	v_lshlrev_b32_e32 v172, 16, v138
	v_and_b32_e32 v173, 0xffff0000, v138
	v_lshlrev_b32_e32 v178, 16, v139
	v_and_b32_e32 v179, 0xffff0000, v139
	v_lshlrev_b32_e32 v176, 16, v132
	v_and_b32_e32 v177, 0xffff0000, v132
	v_lshlrev_b32_e32 v198, 16, v133
	v_and_b32_e32 v199, 0xffff0000, v133
	v_lshlrev_b32_e32 v196, 16, v134
	v_and_b32_e32 v197, 0xffff0000, v134
	v_lshlrev_b32_e32 v202, 16, v135
	v_and_b32_e32 v203, 0xffff0000, v135
	v_lshlrev_b32_e32 v204, 16, v130
	v_and_b32_e32 v205, 0xffff0000, v130
	v_lshlrev_b32_e32 v208, 16, v131
	v_and_b32_e32 v209, 0xffff0000, v131
	global_load_dwordx4 v[140:143], v[128:129], off
	global_load_dwordx4 v[136:139], v[128:129], off offset:64
	global_load_dwordx4 v[132:135], v[128:129], off offset:128
	s_nop 0
	global_load_dwordx4 v[128:131], v[128:129], off offset:192
	v_add_f32_e32 v157, 0, v160
	v_add_f32_e32 v157, v157, v161
	v_add_f32_e32 v157, v157, v164
	v_add_f32_e32 v157, v157, v165
	v_add_f32_e32 v157, v157, v162
	v_add_f32_e32 v157, v157, v163
	v_add_f32_e32 v157, v157, v170
	v_add_f32_e32 v157, v157, v171
	v_add_f32_e32 v157, v157, v166
	v_add_f32_e32 v157, v157, v167
	v_add_f32_e32 v157, v157, v174
	v_add_f32_e32 v157, v157, v175
	v_add_f32_e32 v157, v157, v172
	v_add_f32_e32 v157, v157, v173
	v_add_f32_e32 v157, v157, v178
	v_add_f32_e32 v157, v157, v179
	v_add_f32_e32 v157, v157, v176
	v_add_f32_e32 v157, v157, v177
	v_add_f32_e32 v157, v157, v198
	v_add_f32_e32 v157, v157, v199
	v_add_f32_e32 v157, v157, v196
	v_add_f32_e32 v157, v157, v197
	v_add_f32_e32 v157, v157, v202
	v_add_f32_e32 v157, v157, v203
	v_add_f32_e32 v157, v157, v200
	v_add_f32_e32 v157, v157, v201
	v_add_f32_e32 v157, v157, v206
	v_add_f32_e32 v157, v157, v207
	v_add_f32_e32 v157, v157, v204
	v_add_f32_e32 v157, v157, v205
	v_add_f32_e32 v157, v157, v208
	v_add_f32_e32 v157, v157, v209
	v_mov_b32_e32 v168, v157
	s_nop 1
	v_permlane16_swap_b32_e32 v157, v168
	v_add_f32_e32 v157, v157, v168
	v_mov_b32_e32 v168, v157
	s_nop 1
	v_permlane32_swap_b32_e32 v157, v168
	s_and_saveexec_b64 s[8:9], s[4:5]
	s_cbranch_execz .LBB0_803
	v_add_f32_e32 v157, v157, v168
	ds_write_b32 v217, v157
.LBB0_803:
	s_or_b64 exec, exec, s[8:9]
	s_waitcnt lgkmcnt(0)
	s_barrier
	ds_read2_b32 v[168:169], v214 offset1:16
	ds_read2_b32 v[180:181], v214 offset0:32 offset1:48
	ds_read2_b32 v[182:183], v214 offset0:64 offset1:80
	s_waitcnt lgkmcnt(2)
	v_add_f32_e32 v157, 0, v168
	v_add_f32_e32 v157, v157, v169
	ds_read2_b32 v[168:169], v214 offset0:96 offset1:112
	s_waitcnt lgkmcnt(2)
	v_add_f32_e32 v157, v157, v180
	v_add_f32_e32 v157, v157, v181
	s_waitcnt lgkmcnt(1)
	v_add_f32_e32 v157, v157, v182
	v_add_f32_e32 v157, v157, v183
	s_waitcnt lgkmcnt(0)
	v_add_f32_e32 v157, v157, v168
	v_add_f32_e32 v157, v157, v169
	v_mul_f32_e32 v168, 0x3a800000, v157
	v_pk_add_f32 v[190:191], v[160:161], v[168:169] op_sel_hi:[1,0] neg_lo:[0,1] neg_hi:[0,1]
	v_pk_add_f32 v[188:189], v[164:165], v[168:169] op_sel_hi:[1,0] neg_lo:[0,1] neg_hi:[0,1]
	v_pk_mul_f32 v[224:225], v[190:191], v[190:191]
	v_pk_mul_f32 v[226:227], v[188:189], v[188:189]
	v_add_f32_e32 v157, v224, v225
	v_pk_add_f32 v[194:195], v[162:163], v[168:169] op_sel_hi:[1,0] neg_lo:[0,1] neg_hi:[0,1]
	v_add_f32_e32 v157, v226, v157
	v_pk_mul_f32 v[228:229], v[194:195], v[194:195]
	v_add_f32_e32 v157, v227, v157
	v_pk_add_f32 v[192:193], v[170:171], v[168:169] op_sel_hi:[1,0] neg_lo:[0,1] neg_hi:[0,1]
	v_add_f32_e32 v157, v228, v157
	v_pk_mul_f32 v[170:171], v[192:193], v[192:193]
	v_add_f32_e32 v157, v229, v157
	v_pk_add_f32 v[182:183], v[166:167], v[168:169] op_sel_hi:[1,0] neg_lo:[0,1] neg_hi:[0,1]
	v_add_f32_e32 v157, v170, v157
	v_pk_mul_f32 v[230:231], v[182:183], v[182:183]
	v_add_f32_e32 v157, v171, v157
	v_pk_add_f32 v[180:181], v[174:175], v[168:169] op_sel_hi:[1,0] neg_lo:[0,1] neg_hi:[0,1]
	v_add_f32_e32 v157, v230, v157
	v_pk_mul_f32 v[234:235], v[180:181], v[180:181]
	v_add_f32_e32 v157, v231, v157
	v_pk_add_f32 v[186:187], v[172:173], v[168:169] op_sel_hi:[1,0] neg_lo:[0,1] neg_hi:[0,1]
	v_add_f32_e32 v157, v234, v157
	v_pk_mul_f32 v[238:239], v[186:187], v[186:187]
	v_add_f32_e32 v157, v235, v157
	v_pk_add_f32 v[184:185], v[178:179], v[168:169] op_sel_hi:[1,0] neg_lo:[0,1] neg_hi:[0,1]
	v_add_f32_e32 v157, v238, v157
	v_pk_mul_f32 v[240:241], v[184:185], v[184:185]
	v_add_f32_e32 v157, v239, v157
	v_pk_add_f32 v[174:175], v[176:177], v[168:169] op_sel_hi:[1,0] neg_lo:[0,1] neg_hi:[0,1]
	v_add_f32_e32 v157, v240, v157
	v_pk_mul_f32 v[242:243], v[174:175], v[174:175]
	v_add_f32_e32 v157, v241, v157
	v_pk_add_f32 v[172:173], v[198:199], v[168:169] op_sel_hi:[1,0] neg_lo:[0,1] neg_hi:[0,1]
	v_add_f32_e32 v157, v242, v157
	v_pk_mul_f32 v[198:199], v[172:173], v[172:173]
	v_add_f32_e32 v157, v243, v157
	v_pk_add_f32 v[178:179], v[196:197], v[168:169] op_sel_hi:[1,0] neg_lo:[0,1] neg_hi:[0,1]
	v_add_f32_e32 v157, v198, v157
	v_pk_mul_f32 v[196:197], v[178:179], v[178:179]
	v_add_f32_e32 v157, v199, v157
	v_pk_add_f32 v[176:177], v[202:203], v[168:169] op_sel_hi:[1,0] neg_lo:[0,1] neg_hi:[0,1]
	v_add_f32_e32 v157, v196, v157
	v_pk_mul_f32 v[202:203], v[176:177], v[176:177]
	v_add_f32_e32 v157, v197, v157
	v_pk_add_f32 v[162:163], v[200:201], v[168:169] op_sel_hi:[1,0] neg_lo:[0,1] neg_hi:[0,1]
	v_add_f32_e32 v157, v202, v157
	v_pk_mul_f32 v[200:201], v[162:163], v[162:163]
	v_add_f32_e32 v157, v203, v157
	v_pk_add_f32 v[160:161], v[206:207], v[168:169] op_sel_hi:[1,0] neg_lo:[0,1] neg_hi:[0,1]
	v_add_f32_e32 v157, v200, v157
	v_pk_mul_f32 v[206:207], v[160:161], v[160:161]
	v_add_f32_e32 v157, v201, v157
	v_pk_add_f32 v[166:167], v[204:205], v[168:169] op_sel_hi:[1,0] neg_lo:[0,1] neg_hi:[0,1]
	v_add_f32_e32 v157, v206, v157
	v_pk_mul_f32 v[204:205], v[166:167], v[166:167]
	v_add_f32_e32 v157, v207, v157
	v_pk_add_f32 v[164:165], v[208:209], v[168:169] op_sel_hi:[1,0] neg_lo:[0,1] neg_hi:[0,1]
	v_add_f32_e32 v157, v204, v157
	v_pk_mul_f32 v[208:209], v[164:165], v[164:165]
	v_add_f32_e32 v157, v205, v157
	v_add_f32_e32 v157, v208, v157
	v_add_f32_e32 v157, v209, v157
	v_mov_b32_e32 v169, v157
	s_nop 1
	v_permlane16_swap_b32_e32 v157, v169
	v_add_f32_e32 v157, v157, v169
	v_mov_b32_e32 v169, v157
	s_nop 1
	v_permlane32_swap_b32_e32 v157, v169
	s_and_saveexec_b64 s[8:9], s[4:5]
	s_cbranch_execz .LBB0_805
	v_add_f32_e32 v157, v157, v169
	ds_write_b32 v217, v157 offset:512
.LBB0_805:
	s_or_b64 exec, exec, s[8:9]
	s_waitcnt lgkmcnt(0)
	s_barrier
	ds_read2_b32 v[170:171], v214 offset0:128 offset1:144
	ds_read2_b32 v[244:245], v214 offset0:160 offset1:176
	ds_read2_b32 v[246:247], v214 offset0:192 offset1:208
	ds_read2_b32 v[248:249], v214 offset0:224 offset1:240
	s_waitcnt lgkmcnt(3)
	v_add_f32_e32 v157, 0, v170
	v_add_f32_e32 v157, v157, v171
	s_waitcnt lgkmcnt(2)
	v_add_f32_e32 v157, v157, v244
	v_add_f32_e32 v157, v157, v245
	s_waitcnt lgkmcnt(1)
	v_add_f32_e32 v157, v157, v246
	v_add_f32_e32 v157, v157, v247
	s_waitcnt lgkmcnt(0)
	v_add_f32_e32 v157, v157, v248
	v_add_f32_e32 v157, v157, v249
	v_fmamk_f32 v157, v157, 0x3a800000, v251
	v_cmp_gt_f32_e32 vcc, s19, v157
	v_mul_f32_e32 v169, 0x4f800000, v157
	s_nop 0
	v_cndmask_b32_e32 v157, v157, v169, vcc
	v_sqrt_f32_e32 v169, v157
	s_nop 0
	v_add_u32_e32 v170, -1, v169
	v_fma_f32 v171, -v170, v169, v157
	v_cmp_ge_f32_e64 s[8:9], 0, v171
	v_add_u32_e32 v171, 1, v169
	s_nop 0
	v_cndmask_b32_e64 v170, v169, v170, s[8:9]
	v_fma_f32 v169, -v171, v169, v157
	v_cmp_lt_f32_e64 s[8:9], 0, v169
	s_nop 1
	v_cndmask_b32_e64 v169, v170, v171, s[8:9]
	v_mul_f32_e32 v170, 0x37800000, v169
	v_cndmask_b32_e32 v169, v169, v170, vcc
	v_cmp_class_f32_e32 vcc, v157, v252
	s_nop 1
	v_cndmask_b32_e32 v157, v169, v157, vcc
	v_div_scale_f32 v169, s[8:9], v157, v157, 1.0
	v_rcp_f32_e32 v170, v169
	s_nop 0
	v_fma_f32 v171, -v169, v170, 1.0
	v_fmac_f32_e32 v170, v171, v170
	v_div_scale_f32 v171, vcc, 1.0, v157, 1.0
	v_mul_f32_e32 v196, v171, v170
	v_fma_f32 v197, -v169, v196, v171
	v_fmac_f32_e32 v196, v197, v170
	v_fma_f32 v169, -v169, v196, v171
	v_div_fmas_f32 v169, v169, v170, v196
	v_div_fixup_f32 v170, v169, v157, 1.0
	s_and_saveexec_b64 s[8:9], s[78:79]
	s_cbranch_execz .LBB0_800
	v_mov_b32_e32 v169, v170
	v_lshl_add_u64 v[196:197], v[158:159], 3, s[30:31]
	global_store_dwordx2 v[196:197], v[168:169], off
	s_branch .LBB0_800
.LBB0_807:
	s_waitcnt vmcnt(4)
	v_lshlrev_b32_e32 v158, 16, v140
	v_and_b32_e32 v159, 0xffff0000, v140
	v_lshlrev_b32_e32 v184, 16, v130
	v_and_b32_e32 v185, 0xffff0000, v130
	v_add_f32_e32 v130, 0, v158
	v_lshlrev_b32_e32 v140, 16, v141
	v_add_f32_e32 v130, v130, v159
	v_and_b32_e32 v141, 0xffff0000, v141
	v_add_f32_e32 v130, v130, v140
	v_lshlrev_b32_e32 v160, 16, v142
	v_add_f32_e32 v130, v130, v141
	v_and_b32_e32 v161, 0xffff0000, v142
	v_add_f32_e32 v130, v130, v160
	v_lshlrev_b32_e32 v142, 16, v143
	v_add_f32_e32 v130, v130, v161
	v_and_b32_e32 v143, 0xffff0000, v143
	v_add_f32_e32 v130, v130, v142
	v_lshlrev_b32_e32 v162, 16, v136
	v_add_f32_e32 v130, v130, v143
	v_and_b32_e32 v163, 0xffff0000, v136
	v_add_f32_e32 v130, v130, v162
	v_lshlrev_b32_e32 v166, 16, v137
	v_add_f32_e32 v130, v130, v163
	v_and_b32_e32 v167, 0xffff0000, v137
	v_add_f32_e32 v130, v130, v166
	v_lshlrev_b32_e32 v168, 16, v138
	v_add_f32_e32 v130, v130, v167
	v_and_b32_e32 v169, 0xffff0000, v138
	v_add_f32_e32 v130, v130, v168
	v_lshlrev_b32_e32 v138, 16, v139
	v_add_f32_e32 v130, v130, v169
	v_and_b32_e32 v139, 0xffff0000, v139
	v_add_f32_e32 v130, v130, v138
	v_lshlrev_b32_e32 v178, 16, v132
	v_add_f32_e32 v130, v130, v139
	v_and_b32_e32 v179, 0xffff0000, v132
	v_add_f32_e32 v130, v130, v178
	v_lshlrev_b32_e32 v132, 16, v133
	v_add_f32_e32 v130, v130, v179
	v_and_b32_e32 v133, 0xffff0000, v133
	v_add_f32_e32 v130, v130, v132
	v_lshlrev_b32_e32 v180, 16, v134
	v_add_f32_e32 v130, v130, v133
	v_and_b32_e32 v181, 0xffff0000, v134
	v_add_f32_e32 v130, v130, v180
	v_lshlrev_b32_e32 v134, 16, v135
	v_add_f32_e32 v130, v130, v181
	v_and_b32_e32 v135, 0xffff0000, v135
	v_add_f32_e32 v130, v130, v134
	v_lshlrev_b32_e32 v182, 16, v128
	v_add_f32_e32 v130, v130, v135
	v_and_b32_e32 v183, 0xffff0000, v128
	v_add_f32_e32 v130, v130, v182
	v_lshlrev_b32_e32 v128, 16, v129
	v_add_f32_e32 v130, v130, v183
	v_and_b32_e32 v129, 0xffff0000, v129
	v_add_f32_e32 v130, v130, v128
	v_add_f32_e32 v130, v130, v129
	v_add_f32_e32 v130, v130, v184
	v_lshlrev_b32_e32 v186, 16, v131
	v_add_f32_e32 v130, v130, v185
	v_and_b32_e32 v187, 0xffff0000, v131
	v_add_f32_e32 v130, v130, v186
	v_add_f32_e32 v130, v130, v187
	v_mov_b32_e32 v131, v130
	s_nop 1
	v_permlane16_swap_b32_e32 v130, v131
	v_add_f32_e32 v130, v130, v131
	v_mov_b32_e32 v131, v130
	s_nop 1
	v_permlane32_swap_b32_e32 v130, v131
	s_and_saveexec_b64 s[8:9], s[4:5]
	s_cbranch_execz .LBB0_809
	v_add_f32_e32 v130, v130, v131
	ds_write_b32 v217, v130
.LBB0_809:
	s_or_b64 exec, exec, s[8:9]
	s_waitcnt lgkmcnt(0)
	s_barrier
	ds_read2_b32 v[130:131], v214 offset1:16
	ds_read2_b32 v[136:137], v214 offset0:32 offset1:48
	ds_read2_b32 v[164:165], v214 offset0:64 offset1:80
	s_waitcnt lgkmcnt(2)
	v_add_f32_e32 v130, 0, v130
	v_add_f32_e32 v157, v130, v131
	ds_read2_b32 v[130:131], v214 offset0:96 offset1:112
	s_waitcnt lgkmcnt(2)
	v_add_f32_e32 v136, v157, v136
	v_add_f32_e32 v136, v136, v137
	s_waitcnt lgkmcnt(1)
	v_add_f32_e32 v136, v136, v164
	v_add_f32_e32 v136, v136, v165
	s_waitcnt lgkmcnt(0)
	v_add_f32_e32 v130, v136, v130
	v_add_f32_e32 v130, v130, v131
	v_mul_f32_e32 v136, 0x3a800000, v130
	v_pk_add_f32 v[172:173], v[158:159], v[136:137] op_sel_hi:[1,0] neg_lo:[0,1] neg_hi:[0,1]
	v_pk_add_f32 v[170:171], v[140:141], v[136:137] op_sel_hi:[1,0] neg_lo:[0,1] neg_hi:[0,1]
	v_pk_mul_f32 v[190:191], v[172:173], v[172:173]
	v_pk_mul_f32 v[192:193], v[170:171], v[170:171]
	v_pk_add_f32 v[176:177], v[160:161], v[136:137] op_sel_hi:[1,0] neg_lo:[0,1] neg_hi:[0,1]
	v_pk_add_f32 v[174:175], v[142:143], v[136:137] op_sel_hi:[1,0] neg_lo:[0,1] neg_hi:[0,1]
	v_pk_add_f32 v[164:165], v[162:163], v[136:137] op_sel_hi:[1,0] neg_lo:[0,1] neg_hi:[0,1]
	v_pk_add_f32 v[162:163], v[166:167], v[136:137] op_sel_hi:[1,0] neg_lo:[0,1] neg_hi:[0,1]
	v_pk_add_f32 v[168:169], v[168:169], v[136:137] op_sel_hi:[1,0] neg_lo:[0,1] neg_hi:[0,1]
	v_pk_add_f32 v[166:167], v[138:139], v[136:137] op_sel_hi:[1,0] neg_lo:[0,1] neg_hi:[0,1]
	v_pk_add_f32 v[142:143], v[178:179], v[136:137] op_sel_hi:[1,0] neg_lo:[0,1] neg_hi:[0,1]
	v_pk_add_f32 v[140:141], v[132:133], v[136:137] op_sel_hi:[1,0] neg_lo:[0,1] neg_hi:[0,1]
	v_pk_add_f32 v[160:161], v[180:181], v[136:137] op_sel_hi:[1,0] neg_lo:[0,1] neg_hi:[0,1]
	v_pk_add_f32 v[158:159], v[134:135], v[136:137] op_sel_hi:[1,0] neg_lo:[0,1] neg_hi:[0,1]
	v_pk_add_f32 v[130:131], v[182:183], v[136:137] op_sel_hi:[1,0] neg_lo:[0,1] neg_hi:[0,1]
	v_pk_add_f32 v[128:129], v[128:129], v[136:137] op_sel_hi:[1,0] neg_lo:[0,1] neg_hi:[0,1]
	v_pk_add_f32 v[134:135], v[184:185], v[136:137] op_sel_hi:[1,0] neg_lo:[0,1] neg_hi:[0,1]
	v_pk_add_f32 v[132:133], v[186:187], v[136:137] op_sel_hi:[1,0] neg_lo:[0,1] neg_hi:[0,1]
	v_add_f32_e32 v137, v190, v191
	v_add_f32_e32 v137, v192, v137
	v_pk_mul_f32 v[194:195], v[176:177], v[176:177]
	v_add_f32_e32 v137, v193, v137
	v_add_f32_e32 v137, v194, v137
	v_pk_mul_f32 v[196:197], v[174:175], v[174:175]
	v_add_f32_e32 v137, v195, v137
	v_add_f32_e32 v137, v196, v137
	v_pk_mul_f32 v[198:199], v[164:165], v[164:165]
	v_add_f32_e32 v137, v197, v137
	v_add_f32_e32 v137, v198, v137
	v_pk_mul_f32 v[200:201], v[162:163], v[162:163]
	v_add_f32_e32 v137, v199, v137
	v_add_f32_e32 v137, v200, v137
	v_pk_mul_f32 v[202:203], v[168:169], v[168:169]
	v_add_f32_e32 v137, v201, v137
	v_add_f32_e32 v137, v202, v137
	v_pk_mul_f32 v[138:139], v[166:167], v[166:167]
	v_add_f32_e32 v137, v203, v137
	v_add_f32_e32 v137, v138, v137
	v_pk_mul_f32 v[178:179], v[142:143], v[142:143]
	v_add_f32_e32 v137, v139, v137
	v_add_f32_e32 v137, v178, v137
	v_pk_mul_f32 v[204:205], v[140:141], v[140:141]
	v_add_f32_e32 v137, v179, v137
	v_add_f32_e32 v137, v204, v137
	v_pk_mul_f32 v[180:181], v[160:161], v[160:161]
	v_add_f32_e32 v137, v205, v137
	v_add_f32_e32 v137, v180, v137
	v_pk_mul_f32 v[206:207], v[158:159], v[158:159]
	v_add_f32_e32 v137, v181, v137
	v_add_f32_e32 v137, v206, v137
	v_pk_mul_f32 v[182:183], v[130:131], v[130:131]
	v_add_f32_e32 v137, v207, v137
	v_add_f32_e32 v137, v182, v137
	v_pk_mul_f32 v[208:209], v[128:129], v[128:129]
	v_add_f32_e32 v137, v183, v137
	v_add_f32_e32 v137, v208, v137
	v_pk_mul_f32 v[184:185], v[134:135], v[134:135]
	v_add_f32_e32 v137, v209, v137
	v_add_f32_e32 v137, v184, v137
	v_pk_mul_f32 v[186:187], v[132:133], v[132:133]
	v_add_f32_e32 v137, v185, v137
	v_add_f32_e32 v137, v186, v137
	v_add_f32_e32 v137, v187, v137
	v_mov_b32_e32 v138, v137
	s_nop 1
	v_permlane16_swap_b32_e32 v137, v138
	v_add_f32_e32 v137, v137, v138
	v_mov_b32_e32 v138, v137
	s_nop 1
	v_permlane32_swap_b32_e32 v137, v138
	s_and_saveexec_b64 s[8:9], s[4:5]
	s_cbranch_execz .LBB0_811
	v_add_f32_e32 v137, v137, v138
	ds_write_b32 v217, v137 offset:512
.LBB0_811:
	s_or_b64 exec, exec, s[8:9]
	s_waitcnt lgkmcnt(0)
	s_barrier
	ds_read2_b32 v[138:139], v214 offset0:128 offset1:144
	ds_read2_b32 v[244:245], v214 offset0:160 offset1:176
	ds_read2_b32 v[246:247], v214 offset0:192 offset1:208
	ds_read2_b32 v[248:249], v214 offset0:224 offset1:240
	v_or_b32_e32 v156, 0x70, v156
	v_ashrrev_i32_e32 v157, 31, v156
	s_waitcnt lgkmcnt(3)
	v_add_f32_e32 v137, 0, v138
	v_add_f32_e32 v137, v137, v139
	s_waitcnt lgkmcnt(2)
	v_add_f32_e32 v137, v137, v244
	v_add_f32_e32 v137, v137, v245
	s_waitcnt lgkmcnt(1)
	v_add_f32_e32 v137, v137, v246
	v_add_f32_e32 v137, v137, v247
	s_waitcnt lgkmcnt(0)
	v_add_f32_e32 v137, v137, v248
	v_add_f32_e32 v137, v137, v249
	v_fmamk_f32 v137, v137, 0x3a800000, v251
	v_cmp_gt_f32_e32 vcc, s19, v137
	v_mul_f32_e32 v138, 0x4f800000, v137
	s_nop 0
	v_cndmask_b32_e32 v137, v137, v138, vcc
	v_sqrt_f32_e32 v138, v137
	s_nop 0
	v_add_u32_e32 v139, -1, v138
	v_fma_f32 v178, -v139, v138, v137
	v_cmp_ge_f32_e64 s[8:9], 0, v178
	v_add_u32_e32 v178, 1, v138
	s_nop 0
	v_cndmask_b32_e64 v139, v138, v139, s[8:9]
	v_fma_f32 v138, -v178, v138, v137
	v_cmp_lt_f32_e64 s[8:9], 0, v138
	s_nop 1
	v_cndmask_b32_e64 v138, v139, v178, s[8:9]
	v_mul_f32_e32 v139, 0x37800000, v138
	v_cndmask_b32_e32 v138, v138, v139, vcc
	v_cmp_class_f32_e32 vcc, v137, v252
	s_nop 1
	v_cndmask_b32_e32 v137, v138, v137, vcc
	v_div_scale_f32 v138, s[8:9], v137, v137, 1.0
	v_rcp_f32_e32 v139, v138
	s_nop 0
	v_fma_f32 v178, -v138, v139, 1.0
	v_fmac_f32_e32 v139, v178, v139
	v_div_scale_f32 v178, vcc, 1.0, v137, 1.0
	v_mul_f32_e32 v179, v178, v139
	v_fma_f32 v180, -v138, v179, v178
	v_fmac_f32_e32 v179, v180, v139
	v_fma_f32 v138, -v138, v179, v178
	v_div_fmas_f32 v138, v138, v139, v179
	v_div_fixup_f32 v138, v138, v137, 1.0
	s_and_saveexec_b64 s[8:9], s[78:79]
	s_cbranch_execz .LBB0_813
	v_mov_b32_e32 v137, v138
	v_lshl_add_u64 v[178:179], v[156:157], 3, s[30:31]
	global_store_dwordx2 v[178:179], v[136:137], off
